# P6 prompt role: the drain of the unit's output stores at the end of each unit is removed (they retire under the next unit's prologue; the phase-end barrier still drains)
# speedup vs baseline: 1.0026x; 1.0026x over previous
.LBB0_971:
	s_or_b64 exec, exec, s[8:9]
	v_lshlrev_b32_e32 v178, 11, v37
	v_lshl_add_u64 v[36:37], s[78:79], 0, v[178:179]
	v_lshl_add_u64 v[34:35], v[34:35], 1, v[36:37]
	v_cvt_pk_bf16_f32 v18, v18, v19
	v_cvt_pk_bf16_f32 v19, v20, v21
	v_cvt_pk_bf16_f32 v2, v2, v3
	v_cvt_pk_bf16_f32 v3, v4, v5
	global_store_dwordx2 v[34:35], v[18:19], off offset:1024
	v_cvt_pk_bf16_f32 v18, v22, v23
	v_cvt_pk_bf16_f32 v19, v24, v25
	global_store_dwordx2 v[34:35], v[2:3], off offset:1088
	v_cvt_pk_bf16_f32 v2, v6, v7
	v_cvt_pk_bf16_f32 v3, v8, v9
	global_store_dwordx2 v[34:35], v[18:19], off offset:1040
	v_cvt_pk_bf16_f32 v18, v26, v27
	v_cvt_pk_bf16_f32 v19, v28, v29
	global_store_dwordx2 v[34:35], v[2:3], off offset:1104
	v_cvt_pk_bf16_f32 v2, v10, v11
	v_cvt_pk_bf16_f32 v3, v12, v13
	global_store_dwordx2 v[34:35], v[18:19], off offset:1056
	v_cvt_pk_bf16_f32 v18, v30, v31
	v_cvt_pk_bf16_f32 v19, v32, v33
	global_store_dwordx2 v[34:35], v[2:3], off offset:1120
	v_cvt_pk_bf16_f32 v2, v14, v15
	v_cvt_pk_bf16_f32 v3, v16, v17
	global_store_dwordx2 v[34:35], v[18:19], off offset:1072
	global_store_dwordx2 v[34:35], v[2:3], off offset:1136
	s_mov_b64 s[6:7], 0
	s_and_b64 vcc, exec, s[38:39]
	s_cbranch_vccnz .LBB0_969
